# hand-pipelined GQA attention inner loop added (exp/cvt interleaved with MFMAs); same numerics
# speedup vs baseline: 1.0242x; 1.0069x over previous
.LBB0_538:
	v_add_f32_e32 v233, v233, v249
	v_add_f32_e32 v245, v245, v248
	v_lshl_add_u64 v[206:207], v[206:207], 0, s[28:29]
	s_cmpk_lg_i32 s17, 0x100
	v_lshl_add_u64 v[208:209], v[208:209], 0, s[26:27]
	s_waitcnt lgkmcnt(0)
	s_barrier
	s_cbranch_scc0 .LBB0_540
	s_mov_b32 s14, s17
	s_cmpk_lg_i32 s14, 0xfe
	s_cselect_b64 s[38:39], -1, 0
	s_cmpk_eq_i32 s14, 0xfe
	s_branch .Lgq_loop
.Lgq_loop:
	s_and_b32 s12, s14, 2
	s_mulk_i32 s12, 0x2400
	s_add_i32 s17, s12, 0
	v_add3_u32 v248, s17, v200, v244
	v_add3_u32 v249, s17, v242, v200
	ds_read_b128 v[210:213], v248
	ds_read_b128 v[214:217], v248 offset:32
	ds_read_b128 v[218:221], v248 offset:64
	ds_read_b128 v[222:225], v248 offset:96
	s_cmpk_eq_i32 s14, 0xfe
	s_cbranch_scc1 .Lgq_noload
	global_load_dwordx4 v[160:163], v[206:207], off
	global_load_dwordx4 v[164:167], v[208:209], off
.Lgq_noload:
	s_waitcnt lgkmcnt(3)
	v_mfma_f32_32x32x16_bf16 v[144:159], v[210:213], v[168:171], v[80:95]
	s_waitcnt lgkmcnt(2)
	v_mfma_f32_32x32x16_bf16 v[144:159], v[214:217], v[172:175], v[144:159]
	s_waitcnt lgkmcnt(1)
	v_mfma_f32_32x32x16_bf16 v[144:159], v[218:221], v[176:179], v[144:159]
	s_waitcnt lgkmcnt(0)
	v_mfma_f32_32x32x16_bf16 v[144:159], v[222:225], v[180:183], v[144:159]
	v_mfma_f32_32x32x16_bf16 v[112:127], v[210:213], v[184:187], v[64:79]
	ds_read_b128 v[210:213], v248 offset:4608
	s_nop 9
	v_exp_f32_e32 v144, v144
	v_exp_f32_e32 v145, v145
	v_exp_f32_e32 v146, v146
	v_exp_f32_e32 v147, v147
	v_add_f32_e32 v226, v144, v146
	v_mfma_f32_32x32x16_bf16 v[112:127], v[214:217], v[188:191], v[112:127]
	ds_read_b128 v[214:217], v248 offset:4640
	v_add_f32_e32 v227, v145, v147
	v_exp_f32_e32 v148, v148
	v_exp_f32_e32 v149, v149
	v_add_f32_e32 v226, v226, v148
	v_add_f32_e32 v227, v227, v149
	v_exp_f32_e32 v150, v150
	v_mfma_f32_32x32x16_bf16 v[112:127], v[218:221], v[192:195], v[112:127]
	ds_read_b128 v[218:221], v248 offset:4672
	v_exp_f32_e32 v151, v151
	v_add_f32_e32 v226, v226, v150
	v_add_f32_e32 v227, v227, v151
	v_exp_f32_e32 v152, v152
	v_exp_f32_e32 v153, v153
	v_add_f32_e32 v226, v226, v152
	v_mfma_f32_32x32x16_bf16 v[112:127], v[222:225], v[196:199], v[112:127]
	ds_read_b128 v[222:225], v248 offset:4704
	v_add_f32_e32 v227, v227, v153
	v_exp_f32_e32 v154, v154
	v_exp_f32_e32 v155, v155
	v_add_f32_e32 v226, v226, v154
	v_add_f32_e32 v227, v227, v155
	v_exp_f32_e32 v156, v156
	s_waitcnt lgkmcnt(3)
	v_mfma_f32_32x32x16_bf16 v[128:143], v[210:213], v[168:171], v[80:95]
	v_exp_f32_e32 v157, v157
	v_add_f32_e32 v226, v226, v156
	v_add_f32_e32 v227, v227, v157
	v_exp_f32_e32 v158, v158
	v_exp_f32_e32 v159, v159
	v_add_f32_e32 v226, v226, v158
	s_waitcnt lgkmcnt(2)
	v_mfma_f32_32x32x16_bf16 v[128:143], v[214:217], v[172:175], v[128:143]
	v_add_f32_e32 v227, v227, v159
	v_exp_f32_e32 v112, v112
	v_exp_f32_e32 v113, v113
	v_exp_f32_e32 v114, v114
	v_exp_f32_e32 v115, v115
	s_waitcnt lgkmcnt(1)
	v_mfma_f32_32x32x16_bf16 v[128:143], v[218:221], v[176:179], v[128:143]
	v_add_f32_e32 v228, v112, v114
	v_add_f32_e32 v229, v113, v115
	v_exp_f32_e32 v116, v116
	v_exp_f32_e32 v117, v117
	v_add_f32_e32 v228, v228, v116
	v_add_f32_e32 v229, v229, v117
	v_exp_f32_e32 v118, v118
	s_waitcnt lgkmcnt(0)
	v_mfma_f32_32x32x16_bf16 v[128:143], v[222:225], v[180:183], v[128:143]
	v_exp_f32_e32 v119, v119
	v_add_f32_e32 v228, v228, v118
	v_add_f32_e32 v229, v229, v119
	v_cvt_pk_bf16_f32 v144, v144, v145
	v_cvt_pk_bf16_f32 v145, v146, v147
	v_cvt_pk_bf16_f32 v146, v148, v149
	v_cvt_pk_bf16_f32 v147, v150, v151
	v_cvt_pk_bf16_f32 v112, v112, v113
	v_mfma_f32_32x32x16_bf16 v[96:111], v[210:213], v[184:187], v[64:79]
	ds_read_b128 v[210:213], v249 offset:9216
	v_cvt_pk_bf16_f32 v113, v114, v115
	v_cvt_pk_bf16_f32 v114, v116, v117
	v_cvt_pk_bf16_f32 v115, v118, v119
	v_exp_f32_e32 v120, v120
	v_exp_f32_e32 v121, v121
	v_add_f32_e32 v228, v228, v120
	v_add_f32_e32 v229, v229, v121
	v_mfma_f32_32x32x16_bf16 v[96:111], v[214:217], v[188:191], v[96:111]
	ds_read_b128 v[214:217], v249 offset:13824
	v_exp_f32_e32 v122, v122
	v_exp_f32_e32 v123, v123
	v_add_f32_e32 v228, v228, v122
	v_add_f32_e32 v229, v229, v123
	v_exp_f32_e32 v124, v124
	v_exp_f32_e32 v125, v125
	v_mfma_f32_32x32x16_bf16 v[96:111], v[218:221], v[192:195], v[96:111]
	ds_read_b128 v[218:221], v249 offset:9248
	v_add_f32_e32 v228, v228, v124
	v_add_f32_e32 v229, v229, v125
	v_exp_f32_e32 v126, v126
	v_exp_f32_e32 v127, v127
	v_add_f32_e32 v228, v228, v126
	v_add_f32_e32 v229, v229, v127
	v_cvt_pk_bf16_f32 v152, v152, v153
	v_mfma_f32_32x32x16_bf16 v[96:111], v[222:225], v[196:199], v[96:111]
	ds_read_b128 v[222:225], v249 offset:13856
	v_cvt_pk_bf16_f32 v153, v154, v155
	v_cvt_pk_bf16_f32 v154, v156, v157
	v_cvt_pk_bf16_f32 v155, v158, v159
	v_cvt_pk_bf16_f32 v120, v120, v121
	v_cvt_pk_bf16_f32 v121, v122, v123
	v_cvt_pk_bf16_f32 v122, v124, v125
	v_cvt_pk_bf16_f32 v123, v126, v127
	v_exp_f32_e32 v128, v128
	s_waitcnt lgkmcnt(3)
	s_nop 1
	v_mfma_f32_32x32x16_bf16 v[48:63], v[210:213], v[144:147], v[48:63]
	v_exp_f32_e32 v129, v129
	v_add_f32_e32 v226, v226, v128
	v_add_f32_e32 v227, v227, v129
	v_exp_f32_e32 v130, v130
	v_exp_f32_e32 v131, v131
	v_add_f32_e32 v226, v226, v130
	v_mfma_f32_32x32x16_bf16 v[16:31], v[210:213], v[112:115], v[16:31]
	ds_read_b128 v[210:213], v249 offset:9280
	v_add_f32_e32 v227, v227, v131
	v_exp_f32_e32 v132, v132
	v_exp_f32_e32 v133, v133
	v_add_f32_e32 v226, v226, v132
	v_add_f32_e32 v227, v227, v133
	v_exp_f32_e32 v134, v134
	s_waitcnt lgkmcnt(3)
	v_mfma_f32_32x32x16_bf16 v[32:47], v[214:217], v[144:147], v[32:47]
	v_exp_f32_e32 v135, v135
	v_add_f32_e32 v226, v226, v134
	v_add_f32_e32 v227, v227, v135
	v_exp_f32_e32 v136, v136
	v_exp_f32_e32 v137, v137
	v_add_f32_e32 v226, v226, v136
	v_mfma_f32_32x32x16_bf16 v[0:15], v[214:217], v[112:115], v[0:15]
	ds_read_b128 v[214:217], v249 offset:13888
	v_add_f32_e32 v227, v227, v137
	v_exp_f32_e32 v138, v138
	v_exp_f32_e32 v139, v139
	v_add_f32_e32 v226, v226, v138
	v_add_f32_e32 v227, v227, v139
	v_exp_f32_e32 v140, v140
	s_waitcnt lgkmcnt(3)
	v_mfma_f32_32x32x16_bf16 v[48:63], v[218:221], v[152:155], v[48:63]
	v_exp_f32_e32 v141, v141
	v_add_f32_e32 v226, v226, v140
	v_add_f32_e32 v227, v227, v141
	v_exp_f32_e32 v142, v142
	v_exp_f32_e32 v143, v143
	v_add_f32_e32 v226, v226, v142
	v_mfma_f32_32x32x16_bf16 v[16:31], v[218:221], v[120:123], v[16:31]
	ds_read_b128 v[218:221], v249 offset:9312
	v_add_f32_e32 v227, v227, v143
	v_exp_f32_e32 v96, v96
	v_exp_f32_e32 v97, v97
	v_add_f32_e32 v228, v228, v96
	v_add_f32_e32 v229, v229, v97
	v_exp_f32_e32 v98, v98
	s_waitcnt lgkmcnt(3)
	v_mfma_f32_32x32x16_bf16 v[32:47], v[222:225], v[152:155], v[32:47]
	v_exp_f32_e32 v99, v99
	v_add_f32_e32 v228, v228, v98
	v_add_f32_e32 v229, v229, v99
	v_exp_f32_e32 v100, v100
	v_exp_f32_e32 v101, v101
	v_add_f32_e32 v228, v228, v100
	v_mfma_f32_32x32x16_bf16 v[0:15], v[222:225], v[120:123], v[0:15]
	ds_read_b128 v[222:225], v249 offset:13920
	v_add_f32_e32 v229, v229, v101
	v_exp_f32_e32 v102, v102
	v_exp_f32_e32 v103, v103
	v_add_f32_e32 v228, v228, v102
	v_add_f32_e32 v229, v229, v103
	v_cvt_pk_bf16_f32 v128, v128, v129
	v_cvt_pk_bf16_f32 v129, v130, v131
	v_cvt_pk_bf16_f32 v130, v132, v133
	v_cvt_pk_bf16_f32 v131, v134, v135
	v_cvt_pk_bf16_f32 v96, v96, v97
	v_cvt_pk_bf16_f32 v97, v98, v99
	v_cvt_pk_bf16_f32 v98, v100, v101
	v_cvt_pk_bf16_f32 v99, v102, v103
	s_waitcnt lgkmcnt(3)
	s_nop 1
	v_mfma_f32_32x32x16_bf16 v[48:63], v[210:213], v[128:131], v[48:63]
	v_exp_f32_e32 v104, v104
	v_exp_f32_e32 v105, v105
	v_add_f32_e32 v228, v228, v104
	v_add_f32_e32 v229, v229, v105
	v_exp_f32_e32 v106, v106
	v_exp_f32_e32 v107, v107
	v_mfma_f32_32x32x16_bf16 v[16:31], v[210:213], v[96:99], v[16:31]
	v_add_f32_e32 v228, v228, v106
	v_add_f32_e32 v229, v229, v107
	v_exp_f32_e32 v108, v108
	v_exp_f32_e32 v109, v109
	v_add_f32_e32 v228, v228, v108
	v_add_f32_e32 v229, v229, v109
	v_exp_f32_e32 v110, v110
	s_waitcnt lgkmcnt(2)
	v_mfma_f32_32x32x16_bf16 v[32:47], v[214:217], v[128:131], v[32:47]
	v_exp_f32_e32 v111, v111
	v_add_f32_e32 v228, v228, v110
	v_add_f32_e32 v229, v229, v111
	v_cvt_pk_bf16_f32 v136, v136, v137
	v_cvt_pk_bf16_f32 v137, v138, v139
	v_cvt_pk_bf16_f32 v138, v140, v141
	v_cvt_pk_bf16_f32 v139, v142, v143
	v_cvt_pk_bf16_f32 v104, v104, v105
	s_nop 1
	v_mfma_f32_32x32x16_bf16 v[0:15], v[214:217], v[96:99], v[0:15]
	v_cvt_pk_bf16_f32 v105, v106, v107
	v_cvt_pk_bf16_f32 v106, v108, v109
	v_cvt_pk_bf16_f32 v107, v110, v111
	v_add_f32_e32 v226, v226, v227
	v_add_f32_e32 v228, v228, v229
	v_lshl_add_u64 v[206:207], v[206:207], 0, s[28:29]
	v_lshl_add_u64 v[208:209], v[208:209], 0, s[26:27]
	v_max_f32_e32 v250, v226, v228
	s_waitcnt lgkmcnt(1)
	v_mfma_f32_32x32x16_bf16 v[48:63], v[218:221], v[136:139], v[48:63]
	v_mfma_f32_32x32x16_bf16 v[16:31], v[218:221], v[104:107], v[16:31]
	s_waitcnt lgkmcnt(0)
	v_mfma_f32_32x32x16_bf16 v[32:47], v[222:225], v[136:139], v[32:47]
	v_mfma_f32_32x32x16_bf16 v[0:15], v[222:225], v[104:107], v[0:15]
	v_cmp_lt_f32_e32 vcc, s33, v250
	s_cbranch_vccz .Lgq_norescale
	s_nop 15
	ds_bpermute_b32 v250, v230, v226
	s_waitcnt lgkmcnt(0)
	v_add_f32_e32 v250, v250, v226
	v_frexp_exp_i32_f32_e32 v250, v250
	v_max_i32_e32 v250, 1, v250
	v_add_u32_e32 v250, -1, v250
	v_cvt_f32_u32_e32 v250, v250
	v_exp_f32_e64 v251, -v250
	v_add_f32_e32 v247, v247, v250
	v_xor_b32_e32 v80, 0x80000000, v247
	v_mul_f32_e32 v245, v245, v251
	v_mul_f32_e32 v226, v226, v251
	v_mul_f32_e32 v48, v48, v251
	v_mul_f32_e32 v49, v49, v251
	v_mul_f32_e32 v50, v50, v251
	v_mul_f32_e32 v51, v51, v251
	v_mul_f32_e32 v52, v52, v251
	v_mul_f32_e32 v53, v53, v251
	v_mul_f32_e32 v54, v54, v251
	v_mul_f32_e32 v55, v55, v251
	v_mul_f32_e32 v56, v56, v251
	v_mul_f32_e32 v57, v57, v251
	v_mul_f32_e32 v58, v58, v251
	v_mul_f32_e32 v59, v59, v251
	v_mul_f32_e32 v60, v60, v251
	v_mul_f32_e32 v61, v61, v251
	v_mul_f32_e32 v62, v62, v251
	v_mul_f32_e32 v63, v63, v251
	v_mul_f32_e32 v32, v32, v251
	v_mul_f32_e32 v33, v33, v251
	v_mul_f32_e32 v34, v34, v251
	v_mul_f32_e32 v35, v35, v251
	v_mul_f32_e32 v36, v36, v251
	v_mul_f32_e32 v37, v37, v251
	v_mul_f32_e32 v38, v38, v251
	v_mul_f32_e32 v39, v39, v251
	v_mul_f32_e32 v40, v40, v251
	v_mul_f32_e32 v41, v41, v251
	v_mul_f32_e32 v42, v42, v251
	v_mul_f32_e32 v43, v43, v251
	v_mul_f32_e32 v44, v44, v251
	v_mul_f32_e32 v45, v45, v251
	v_mul_f32_e32 v46, v46, v251
	v_mul_f32_e32 v47, v47, v251
	v_mov_b32_e32 v81, v80
	v_mov_b32_e32 v82, v80
	v_mov_b32_e32 v83, v80
	v_mov_b32_e32 v84, v80
	v_mov_b32_e32 v85, v80
	v_mov_b32_e32 v86, v80
	v_mov_b32_e32 v87, v80
	v_mov_b32_e32 v88, v80
	v_mov_b32_e32 v89, v80
	v_mov_b32_e32 v90, v80
	v_mov_b32_e32 v91, v80
	v_mov_b32_e32 v92, v80
	v_mov_b32_e32 v93, v80
	v_mov_b32_e32 v94, v80
	v_mov_b32_e32 v95, v80
	ds_bpermute_b32 v250, v230, v228
	s_waitcnt lgkmcnt(0)
	v_add_f32_e32 v250, v250, v228
	v_frexp_exp_i32_f32_e32 v250, v250
	v_max_i32_e32 v250, 1, v250
	v_add_u32_e32 v250, -1, v250
	v_cvt_f32_u32_e32 v250, v250
	v_exp_f32_e64 v251, -v250
	v_add_f32_e32 v246, v246, v250
	v_xor_b32_e32 v64, 0x80000000, v246
	v_mul_f32_e32 v233, v233, v251
	v_mul_f32_e32 v228, v228, v251
	v_mul_f32_e32 v16, v16, v251
	v_mul_f32_e32 v17, v17, v251
	v_mul_f32_e32 v18, v18, v251
	v_mul_f32_e32 v19, v19, v251
	v_mul_f32_e32 v20, v20, v251
	v_mul_f32_e32 v21, v21, v251
	v_mul_f32_e32 v22, v22, v251
	v_mul_f32_e32 v23, v23, v251
	v_mul_f32_e32 v24, v24, v251
	v_mul_f32_e32 v25, v25, v251
	v_mul_f32_e32 v26, v26, v251
	v_mul_f32_e32 v27, v27, v251
	v_mul_f32_e32 v28, v28, v251
	v_mul_f32_e32 v29, v29, v251
	v_mul_f32_e32 v30, v30, v251
	v_mul_f32_e32 v31, v31, v251
	v_mul_f32_e32 v0, v0, v251
	v_mul_f32_e32 v1, v1, v251
	v_mul_f32_e32 v2, v2, v251
	v_mul_f32_e32 v3, v3, v251
	v_mul_f32_e32 v4, v4, v251
	v_mul_f32_e32 v5, v5, v251
	v_mul_f32_e32 v6, v6, v251
	v_mul_f32_e32 v7, v7, v251
	v_mul_f32_e32 v8, v8, v251
	v_mul_f32_e32 v9, v9, v251
	v_mul_f32_e32 v10, v10, v251
	v_mul_f32_e32 v11, v11, v251
	v_mul_f32_e32 v12, v12, v251
	v_mul_f32_e32 v13, v13, v251
	v_mul_f32_e32 v14, v14, v251
	v_mul_f32_e32 v15, v15, v251
	v_mov_b32_e32 v65, v64
	v_mov_b32_e32 v66, v64
	v_mov_b32_e32 v67, v64
	v_mov_b32_e32 v68, v64
	v_mov_b32_e32 v69, v64
	v_mov_b32_e32 v70, v64
	v_mov_b32_e32 v71, v64
	v_mov_b32_e32 v72, v64
	v_mov_b32_e32 v73, v64
	v_mov_b32_e32 v74, v64
	v_mov_b32_e32 v75, v64
	v_mov_b32_e32 v76, v64
	v_mov_b32_e32 v77, v64
	v_mov_b32_e32 v78, v64
	v_mov_b32_e32 v79, v64
.Lgq_norescale:
	v_add_f32_e32 v245, v245, v226
	v_add_f32_e32 v233, v233, v228
	s_add_i32 s14, s14, 2
	s_cmpk_eq_i32 s14, 0x100
	s_cbranch_scc1 .Lgq_last
	s_and_b32 s12, s14, 2
	s_mulk_i32 s12, 0x2400
	v_add_u32_e32 v250, s12, v243
	s_waitcnt vmcnt(1)
	ds_write_b128 v250, v[160:163]
	s_waitcnt vmcnt(0)
	ds_write_b128 v250, v[164:167] offset:9216
	s_waitcnt lgkmcnt(0)
	s_barrier
	s_branch .Lgq_loop
.Lgq_last:
	s_nop 7
	s_waitcnt lgkmcnt(0)
	s_barrier
	s_branch .LBB0_540
.LBB0_540:
	ds_bpermute_b32 v66, v230, v245
	s_lshl_b32 s70, s16, 1
	v_lshlrev_b64 v[64:65], 11, v[204:205]
	v_lshl_add_u64 v[64:65], s[20:21], 0, v[64:65]
	v_lshl_add_u64 v[64:65], v[64:65], 0, s[70:71]
	s_waitcnt lgkmcnt(0)
	v_add_f32_e32 v66, v245, v66
	v_div_scale_f32 v67, s[16:17], v66, v66, 1.0
	v_rcp_f32_e32 v68, v67
	v_div_scale_f32 v69, vcc, 1.0, v66, 1.0
	v_lshlrev_b32_e32 v200, 3, v232
	v_fma_f32 v70, -v67, v68, 1.0
	v_fmac_f32_e32 v68, v70, v68
	v_mul_f32_e32 v70, v69, v68
	v_fma_f32 v71, -v67, v70, v69
	v_fmac_f32_e32 v70, v71, v68
	v_fma_f32 v67, -v67, v70, v69
	v_div_fmas_f32 v67, v67, v68, v70
	v_div_fixup_f32 v66, v67, v66, 1.0
	v_pk_mul_f32 v[32:33], v[32:33], v[66:67] op_sel_hi:[1,0]
	v_pk_mul_f32 v[34:35], v[34:35], v[66:67] op_sel_hi:[1,0]
	v_lshl_add_u64 v[64:65], v[64:65], 0, v[200:201]
	v_cvt_pk_bf16_f32 v32, v32, v33
	v_cvt_pk_bf16_f32 v33, v34, v35
	global_store_dwordx2 v[64:65], v[32:33], off offset:1088
	v_pk_mul_f32 v[32:33], v[36:37], v[66:67] op_sel_hi:[1,0]
	ds_bpermute_b32 v36, v230, v233
	v_pk_mul_f32 v[34:35], v[38:39], v[66:67] op_sel_hi:[1,0]
	v_cvt_pk_bf16_f32 v32, v32, v33
	v_cvt_pk_bf16_f32 v33, v34, v35
	global_store_dwordx2 v[64:65], v[32:33], off offset:1104
	s_waitcnt lgkmcnt(0)
	v_add_f32_e32 v36, v233, v36
	v_div_scale_f32 v37, s[16:17], v36, v36, 1.0
	v_pk_mul_f32 v[32:33], v[40:41], v[66:67] op_sel_hi:[1,0]
	v_pk_mul_f32 v[34:35], v[42:43], v[66:67] op_sel_hi:[1,0]
	v_rcp_f32_e32 v38, v37
	v_cvt_pk_bf16_f32 v32, v32, v33
	v_cvt_pk_bf16_f32 v33, v34, v35
	global_store_dwordx2 v[64:65], v[32:33], off offset:1120
	v_pk_mul_f32 v[32:33], v[44:45], v[66:67] op_sel_hi:[1,0]
	v_pk_mul_f32 v[34:35], v[46:47], v[66:67] op_sel_hi:[1,0]
	v_cvt_pk_bf16_f32 v32, v32, v33
	v_cvt_pk_bf16_f32 v33, v34, v35
	global_store_dwordx2 v[64:65], v[32:33], off offset:1136
	v_fma_f32 v32, -v37, v38, 1.0
	v_fmac_f32_e32 v38, v32, v38
	v_div_scale_f32 v32, vcc, 1.0, v36, 1.0
	v_mul_f32_e32 v33, v32, v38
	v_fma_f32 v34, -v37, v33, v32
	v_fmac_f32_e32 v33, v34, v38
	v_fma_f32 v32, -v37, v33, v32
	v_div_fmas_f32 v32, v32, v38, v33
	v_lshlrev_b64 v[34:35], 11, v[202:203]
	v_div_fixup_f32 v32, v32, v36, 1.0
	v_lshl_add_u64 v[34:35], s[20:21], 0, v[34:35]
	v_pk_mul_f32 v[48:49], v[48:49], v[66:67] op_sel_hi:[1,0]
	v_pk_mul_f32 v[50:51], v[50:51], v[66:67] op_sel_hi:[1,0]
	v_lshl_add_u64 v[34:35], v[34:35], 0, s[70:71]
	v_pk_mul_f32 v[16:17], v[16:17], v[32:33] op_sel_hi:[1,0]
	v_pk_mul_f32 v[18:19], v[18:19], v[32:33] op_sel_hi:[1,0]
	v_pk_mul_f32 v[0:1], v[0:1], v[32:33] op_sel_hi:[1,0]
	v_pk_mul_f32 v[2:3], v[2:3], v[32:33] op_sel_hi:[1,0]
	v_cvt_pk_bf16_f32 v48, v48, v49
	v_cvt_pk_bf16_f32 v49, v50, v51
	v_lshl_add_u64 v[34:35], v[34:35], 0, v[200:201]
	v_cvt_pk_bf16_f32 v16, v16, v17
	v_cvt_pk_bf16_f32 v17, v18, v19
	v_cvt_pk_bf16_f32 v0, v0, v1
	v_cvt_pk_bf16_f32 v1, v2, v3
	global_store_dwordx2 v[64:65], v[48:49], off offset:1024
	v_pk_mul_f32 v[48:49], v[52:53], v[66:67] op_sel_hi:[1,0]
	v_pk_mul_f32 v[50:51], v[54:55], v[66:67] op_sel_hi:[1,0]
	global_store_dwordx2 v[34:35], v[16:17], off offset:1024
	v_pk_mul_f32 v[16:17], v[20:21], v[32:33] op_sel_hi:[1,0]
	v_pk_mul_f32 v[18:19], v[22:23], v[32:33] op_sel_hi:[1,0]
	global_store_dwordx2 v[34:35], v[0:1], off offset:1088
	v_pk_mul_f32 v[0:1], v[4:5], v[32:33] op_sel_hi:[1,0]
	v_pk_mul_f32 v[2:3], v[6:7], v[32:33] op_sel_hi:[1,0]
	v_cvt_pk_bf16_f32 v48, v48, v49
	v_cvt_pk_bf16_f32 v49, v50, v51
	v_cvt_pk_bf16_f32 v16, v16, v17
	v_cvt_pk_bf16_f32 v17, v18, v19
	v_cvt_pk_bf16_f32 v0, v0, v1
	v_cvt_pk_bf16_f32 v1, v2, v3
	global_store_dwordx2 v[64:65], v[48:49], off offset:1040
	v_pk_mul_f32 v[48:49], v[56:57], v[66:67] op_sel_hi:[1,0]
	v_pk_mul_f32 v[50:51], v[58:59], v[66:67] op_sel_hi:[1,0]
	global_store_dwordx2 v[34:35], v[16:17], off offset:1040
	v_pk_mul_f32 v[16:17], v[24:25], v[32:33] op_sel_hi:[1,0]
	v_pk_mul_f32 v[18:19], v[26:27], v[32:33] op_sel_hi:[1,0]
	global_store_dwordx2 v[34:35], v[0:1], off offset:1104
	v_pk_mul_f32 v[0:1], v[8:9], v[32:33] op_sel_hi:[1,0]
	v_pk_mul_f32 v[2:3], v[10:11], v[32:33] op_sel_hi:[1,0]
	v_cvt_pk_bf16_f32 v48, v48, v49
	v_cvt_pk_bf16_f32 v49, v50, v51
	v_cvt_pk_bf16_f32 v16, v16, v17
	v_cvt_pk_bf16_f32 v17, v18, v19
	v_cvt_pk_bf16_f32 v0, v0, v1
	v_cvt_pk_bf16_f32 v1, v2, v3
	global_store_dwordx2 v[64:65], v[48:49], off offset:1056
	v_pk_mul_f32 v[48:49], v[60:61], v[66:67] op_sel_hi:[1,0]
	v_pk_mul_f32 v[50:51], v[62:63], v[66:67] op_sel_hi:[1,0]
	global_store_dwordx2 v[34:35], v[16:17], off offset:1056
	v_pk_mul_f32 v[16:17], v[28:29], v[32:33] op_sel_hi:[1,0]
	v_pk_mul_f32 v[18:19], v[30:31], v[32:33] op_sel_hi:[1,0]
	global_store_dwordx2 v[34:35], v[0:1], off offset:1120
	v_pk_mul_f32 v[0:1], v[12:13], v[32:33] op_sel_hi:[1,0]
	v_pk_mul_f32 v[2:3], v[14:15], v[32:33] op_sel_hi:[1,0]
	v_cvt_pk_bf16_f32 v48, v48, v49
	v_cvt_pk_bf16_f32 v49, v50, v51
	v_cvt_pk_bf16_f32 v16, v16, v17
	v_cvt_pk_bf16_f32 v17, v18, v19
	v_cvt_pk_bf16_f32 v0, v0, v1
	v_cvt_pk_bf16_f32 v1, v2, v3
	s_mov_b64 s[34:35], 0
	v_readlane_b32 s15, v255, 22
	global_store_dwordx2 v[64:65], v[48:49], off offset:1072
	global_store_dwordx2 v[34:35], v[16:17], off offset:1072
	global_store_dwordx2 v[34:35], v[0:1], off offset:1136
